# hyena step loop: ring entries prefetched 2 steps ahead, z vectors 3 steps ahead (4 slots), counted lgkmcnt, VALU interleaved with MFMAs
# speedup vs baseline: 1.0166x; 1.0077x over previous
; __device__ __forceinline__ void hyena_lat_job(const Params& p, char* smem, int l, int c) {
;     ...
;       bf16x8 ring[8];
; #pragma unroll
;       for (int u = 0; u < 8; ++u) {
;         const int k_ = u < 7 ? u : 0;
;         ring[u] = *(const bf16x8*)((const char*)Es + ((be & ~7) + 16 * k_) * 16 + exo[k_ & 3]);
;       }
;       bf16x8 bq0, bq1;
;       {
;         int S = 8 * ib - sc;
;         int za = (S >= 0 && S < 512) ? b * 10240 + (S >> 1) * 40 + (S & 1) * 16 + 8 * h : 32;
;         bq0 = *(const bf16x8*)&zs[za];
;         bq1 = bq0;
;       }
.LBB0_995:
	v_mul_lo_u32 v243, v115, 40
	ds_read_b128 v[66:69], v141 offset:40960
	ds_read_b128 v[70:73], v141 offset:41984
	ds_read_b128 v[78:81], v140 offset:41216
	ds_read_b128 v[86:89], v139 offset:41472
	ds_read_b128 v[90:93], v142 offset:41728
	v_lshl_add_u32 v242, v106, 1, v243
	v_add_u32_e32 v240, 8, v115
	v_cmp_gt_u32_e32 vcc, s55, v240
	v_add_u32_e32 v246, 0x140, v242
	s_nop 1
	v_cndmask_b32_e32 v246, 64, v246, vcc
	v_add_u32_e32 v240, 7, v115
	v_cmp_gt_u32_e32 vcc, s55, v240
	v_add_u32_e32 v247, 0x110, v242
	s_nop 1
	v_cndmask_b32_e32 v247, 64, v247, vcc
	v_add_u32_e32 v240, 6, v115
	v_cmp_gt_u32_e32 vcc, s55, v240
	v_add_u32_e32 v248, 0xf0, v242
	s_nop 1
	v_cndmask_b32_e32 v248, 64, v248, vcc
	v_add_u32_e32 v240, 5, v115
	v_cmp_gt_u32_e32 vcc, s55, v240
	v_add_u32_e32 v241, 0xc0, v242
	s_nop 1
	v_cndmask_b32_e32 v241, 64, v241, vcc
	ds_read_b128 v[74:77], v140 offset:42240
	ds_read_b128 v[98:101], v246
	ds_read_b128 v[82:85], v139 offset:42496
	ds_read_b128 v[102:105], v247
	ds_read_b128 v[94:97], v142 offset:42752
	ds_read_b128 v[224:227], v248
	s_mov_b32 s31, 0
	v_mov_b32_e32 v0, v115
	s_mov_b32 s34, s11
	s_sub_i32 s50, s19, s18
	s_branch .LBB0_997

; __device__ __forceinline__ void hyena_lat_job(const Params& p, char* smem, int l, int c) {
;     ...
;       for (int g8 = 0; g8 < 8; ++g8) {
;         HY_STEP(0, bq0, bq1) HY_STEP(1, bq1, bq0) HY_STEP(2, bq0, bq1) HY_STEP(3, bq1, bq0)
;         HY_STEP(4, bq0, bq1) HY_STEP(5, bq1, bq0) HY_STEP(6, bq0, bq1) HY_STEP(7, bq1, bq0)
.LBB0_997:
	s_sub_i32 s35, s34, s18
	v_add_u32_e32 v146, s31, v142
	v_add_u32_e32 v147, s31, v141
	v_add_u32_e32 v149, s31, v140
	v_add_u32_e32 v148, s31, v139
	s_cmp_gt_u32 s35, s50
	s_cbranch_scc1 .Lhy_skip0
	s_waitcnt lgkmcnt(4)
	v_mfma_f32_32x32x16_bf16 v[50:65], v[66:69], v[98:101], v[50:65]
	ds_read_b128 v[66:69], v147 offset:43008
	ds_read_b128 v[228:231], v241
	v_mfma_f32_32x32x16_bf16 v[34:49], v[86:89], v[98:101], v[34:49]
	v_add_u32_e32 v240, 4, v0
	v_cmp_gt_u32_e32 vcc, s55, v240
	v_add_u32_e32 v241, 0xa0, v242
	v_mfma_f32_32x32x16_bf16 v[18:33], v[70:73], v[98:101], v[18:33]
	s_waitcnt lgkmcnt(5)
	v_mfma_f32_32x32x16_bf16 v[2:17], v[82:85], v[98:101], v[2:17]
	v_cndmask_b32_e32 v241, 64, v241, vcc
	s_branch .Lhy_next0
.Lhy_skip0:
	s_waitcnt lgkmcnt(6)
	ds_read_b128 v[66:69], v147 offset:43008
	ds_read_b128 v[228:231], v241
	v_add_u32_e32 v240, 4, v0
	v_cmp_gt_u32_e32 vcc, s55, v240
	v_add_u32_e32 v241, 0xa0, v242
	s_nop 1
	v_cndmask_b32_e32 v241, 64, v241, vcc
.Lhy_next0:
	s_add_i32 s16, s35, 1
	s_cmp_gt_u32 s16, s50
	s_cbranch_scc1 .Lhy_skip1
	s_waitcnt lgkmcnt(4)
	v_mfma_f32_32x32x16_bf16 v[50:65], v[78:81], v[102:105], v[50:65]
	ds_read_b128 v[78:81], v149 offset:43264
	ds_read_b128 v[98:101], v241
	v_mfma_f32_32x32x16_bf16 v[34:49], v[90:93], v[102:105], v[34:49]
	v_add_u32_e32 v240, 3, v0
	v_cmp_gt_u32_e32 vcc, s55, v240
	v_add_u32_e32 v241, 0x70, v242
	v_mfma_f32_32x32x16_bf16 v[18:33], v[74:77], v[102:105], v[18:33]
	s_waitcnt lgkmcnt(5)
	v_mfma_f32_32x32x16_bf16 v[2:17], v[94:97], v[102:105], v[2:17]
	v_cndmask_b32_e32 v241, 64, v241, vcc
	s_branch .Lhy_next1
.Lhy_skip1:
	s_waitcnt lgkmcnt(6)
	ds_read_b128 v[78:81], v149 offset:43264
	ds_read_b128 v[98:101], v241
	v_add_u32_e32 v240, 3, v0
	v_cmp_gt_u32_e32 vcc, s55, v240
	v_add_u32_e32 v241, 0x70, v242
	s_nop 1
	v_cndmask_b32_e32 v241, 64, v241, vcc
.Lhy_next1:
	s_add_i32 s16, s35, 2
	s_cmp_gt_u32 s16, s50
	s_cbranch_scc1 .Lhy_skip2
	s_waitcnt lgkmcnt(4)
	v_mfma_f32_32x32x16_bf16 v[50:65], v[86:89], v[224:227], v[50:65]
	ds_read_b128 v[86:89], v148 offset:43520
	ds_read_b128 v[102:105], v241
	v_mfma_f32_32x32x16_bf16 v[34:49], v[70:73], v[224:227], v[34:49]
	v_add_u32_e32 v240, 2, v0
	v_cmp_gt_u32_e32 vcc, s55, v240
	v_add_u32_e32 v241, 0x50, v242
	v_mfma_f32_32x32x16_bf16 v[18:33], v[82:85], v[224:227], v[18:33]
	s_waitcnt lgkmcnt(5)
	v_mfma_f32_32x32x16_bf16 v[2:17], v[66:69], v[224:227], v[2:17]
	v_cndmask_b32_e32 v241, 64, v241, vcc
	s_branch .Lhy_next2
.Lhy_skip2:
	s_waitcnt lgkmcnt(6)
	ds_read_b128 v[86:89], v148 offset:43520
	ds_read_b128 v[102:105], v241
	v_add_u32_e32 v240, 2, v0
	v_cmp_gt_u32_e32 vcc, s55, v240
	v_add_u32_e32 v241, 0x50, v242
	s_nop 1
	v_cndmask_b32_e32 v241, 64, v241, vcc
.Lhy_next2:
	s_add_i32 s16, s35, 3
	s_cmp_gt_u32 s16, s50
	s_cbranch_scc1 .Lhy_skip3
	s_waitcnt lgkmcnt(4)
	v_mfma_f32_32x32x16_bf16 v[50:65], v[90:93], v[228:231], v[50:65]
	ds_read_b128 v[90:93], v146 offset:43776
	ds_read_b128 v[224:227], v241
	v_mfma_f32_32x32x16_bf16 v[34:49], v[74:77], v[228:231], v[34:49]
	v_add_u32_e32 v240, 1, v0
	v_cmp_gt_u32_e32 vcc, s55, v240
	v_add_u32_e32 v241, 32, v242
	v_mfma_f32_32x32x16_bf16 v[18:33], v[94:97], v[228:231], v[18:33]
	s_waitcnt lgkmcnt(5)
	v_mfma_f32_32x32x16_bf16 v[2:17], v[78:81], v[228:231], v[2:17]
	v_cndmask_b32_e32 v241, 64, v241, vcc
	s_branch .Lhy_next3
.Lhy_skip3:
	s_waitcnt lgkmcnt(6)
	ds_read_b128 v[90:93], v146 offset:43776
	ds_read_b128 v[224:227], v241
	v_add_u32_e32 v240, 1, v0
	v_cmp_gt_u32_e32 vcc, s55, v240
	v_add_u32_e32 v241, 32, v242
	s_nop 1
	v_cndmask_b32_e32 v241, 64, v241, vcc
; __device__ __forceinline__ void hyena_lat_job(const Params& p, char* smem, int l, int c) {
;     ...
;       for (int g8 = 0; g8 < 8; ++g8) {
;         HY_STEP(0, bq0, bq1) HY_STEP(1, bq1, bq0) HY_STEP(2, bq0, bq1) HY_STEP(3, bq1, bq0)
;         HY_STEP(4, bq0, bq1) HY_STEP(5, bq1, bq0) HY_STEP(6, bq0, bq1) HY_STEP(7, bq1, bq0)
;       }
.Lhy_next3:
	s_add_i32 s16, s35, 4
	s_cmp_gt_u32 s16, s50
	s_cbranch_scc1 .Lhy_skip4
	s_waitcnt lgkmcnt(4)
	v_mfma_f32_32x32x16_bf16 v[50:65], v[70:73], v[98:101], v[50:65]
	ds_read_b128 v[70:73], v147 offset:44032
	ds_read_b128 v[228:231], v241
	v_mfma_f32_32x32x16_bf16 v[34:49], v[82:85], v[98:101], v[34:49]
	v_add_u32_e32 v240, 0, v0
	v_cmp_gt_u32_e32 vcc, s55, v240
	v_add_u32_e32 v241, 0, v242
	v_mfma_f32_32x32x16_bf16 v[18:33], v[66:69], v[98:101], v[18:33]
	s_waitcnt lgkmcnt(5)
	v_mfma_f32_32x32x16_bf16 v[2:17], v[86:89], v[98:101], v[2:17]
	v_cndmask_b32_e32 v241, 64, v241, vcc
	s_branch .Lhy_next4
.Lhy_skip4:
	s_waitcnt lgkmcnt(6)
	ds_read_b128 v[70:73], v147 offset:44032
	ds_read_b128 v[228:231], v241
	v_add_u32_e32 v240, 0, v0
	v_cmp_gt_u32_e32 vcc, s55, v240
	v_add_u32_e32 v241, 0, v242
	s_nop 1
	v_cndmask_b32_e32 v241, 64, v241, vcc
.Lhy_next4:
	s_add_i32 s16, s35, 5
	s_cmp_gt_u32 s16, s50
	s_cbranch_scc1 .Lhy_skip5
	s_waitcnt lgkmcnt(4)
	v_mfma_f32_32x32x16_bf16 v[50:65], v[74:77], v[102:105], v[50:65]
	ds_read_b128 v[74:77], v149 offset:44288
	ds_read_b128 v[98:101], v241
	v_mfma_f32_32x32x16_bf16 v[34:49], v[94:97], v[102:105], v[34:49]
	v_add_u32_e32 v240, -1, v0
	v_cmp_gt_u32_e32 vcc, s55, v240
	v_add_u32_e32 v241, 0xffffffd0, v242
	v_mfma_f32_32x32x16_bf16 v[18:33], v[78:81], v[102:105], v[18:33]
	s_waitcnt lgkmcnt(5)
	v_mfma_f32_32x32x16_bf16 v[2:17], v[90:93], v[102:105], v[2:17]
	v_cndmask_b32_e32 v241, 64, v241, vcc
	s_branch .Lhy_next5
.Lhy_skip5:
	s_waitcnt lgkmcnt(6)
	ds_read_b128 v[74:77], v149 offset:44288
	ds_read_b128 v[98:101], v241
	v_add_u32_e32 v240, -1, v0
	v_cmp_gt_u32_e32 vcc, s55, v240
	v_add_u32_e32 v241, 0xffffffd0, v242
	s_nop 1
	v_cndmask_b32_e32 v241, 64, v241, vcc
.Lhy_next5:
	s_add_i32 s16, s35, 6
	s_cmp_gt_u32 s16, s50
	s_cbranch_scc1 .Lhy_skip6
	s_waitcnt lgkmcnt(4)
	v_mfma_f32_32x32x16_bf16 v[50:65], v[82:85], v[224:227], v[50:65]
	ds_read_b128 v[82:85], v148 offset:44544
	ds_read_b128 v[102:105], v241
	v_mfma_f32_32x32x16_bf16 v[34:49], v[66:69], v[224:227], v[34:49]
	v_add_u32_e32 v240, -2, v0
	v_cmp_gt_u32_e32 vcc, s55, v240
	v_add_u32_e32 v241, 0xffffffb0, v242
	v_mfma_f32_32x32x16_bf16 v[18:33], v[86:89], v[224:227], v[18:33]
	s_waitcnt lgkmcnt(5)
	v_mfma_f32_32x32x16_bf16 v[2:17], v[70:73], v[224:227], v[2:17]
	v_cndmask_b32_e32 v241, 64, v241, vcc
	s_branch .Lhy_next6
.Lhy_skip6:
	s_waitcnt lgkmcnt(6)
	ds_read_b128 v[82:85], v148 offset:44544
	ds_read_b128 v[102:105], v241
	v_add_u32_e32 v240, -2, v0
	v_cmp_gt_u32_e32 vcc, s55, v240
	v_add_u32_e32 v241, 0xffffffb0, v242
	s_nop 1
	v_cndmask_b32_e32 v241, 64, v241, vcc
.Lhy_next6:
	s_add_i32 s16, s35, 7
	s_cmp_gt_u32 s16, s50
	s_cbranch_scc1 .Lhy_skip7
	s_waitcnt lgkmcnt(4)
	v_mfma_f32_32x32x16_bf16 v[50:65], v[94:97], v[228:231], v[50:65]
	ds_read_b128 v[94:97], v146 offset:44800
	ds_read_b128 v[224:227], v241
	v_mfma_f32_32x32x16_bf16 v[34:49], v[78:81], v[228:231], v[34:49]
	v_add_u32_e32 v240, -3, v0
	v_cmp_gt_u32_e32 vcc, s55, v240
	v_add_u32_e32 v241, 0xffffff80, v242
	v_mfma_f32_32x32x16_bf16 v[18:33], v[90:93], v[228:231], v[18:33]
	s_waitcnt lgkmcnt(5)
	v_mfma_f32_32x32x16_bf16 v[2:17], v[74:77], v[228:231], v[2:17]
	v_cndmask_b32_e32 v241, 64, v241, vcc
	s_branch .Lhy_next7
.Lhy_skip7:
	s_waitcnt lgkmcnt(6)
	ds_read_b128 v[94:97], v146 offset:44800
	ds_read_b128 v[224:227], v241
	v_add_u32_e32 v240, -3, v0
	v_cmp_gt_u32_e32 vcc, s55, v240
	v_add_u32_e32 v241, 0xffffff80, v242
	s_nop 1
	v_cndmask_b32_e32 v241, 64, v241, vcc
.Lhy_next7:
	v_add_u32_e32 v242, 0xfffffec0, v242
	s_branch .LBB0_996
